# mix2: L1 prefetch of the 8 dependent row loads at each item head (additive), on top of LRU batch + tail overlap
# speedup vs baseline: 1.0169x; 1.0014x over previous
.LBB0_415:
	flat_load_dwordx2 v[58:59], v[78:79] offset:216
	flat_load_dwordx2 v[60:61], v[78:79] offset:152
	s_and_b32 s37, s3, 63
	s_and_b32 s6, s3, 0xffffffc0
	s_add_i32 s14, s37, 7
	s_ashr_i32 s7, s6, 31
	s_lshr_b32 s16, s14, 3
	s_lshl_b64 s[14:15], s[6:7], 11
	s_mul_i32 s6, s16, s19
	s_add_i32 s7, s6, s16
	s_min_i32 s38, s7, s37
	v_mov_b32_e32 v0, 1.0
	v_mov_b32_e32 v64, 0
	v_mov_b32_e32 v1, 1.0
	v_mov_b32_e32 v65, 0
	v_mov_b32_e32 v62, 1.0
	v_mov_b32_e32 v66, 0
	v_mov_b32_e32 v63, 1.0
	s_cmp_ge_i32 s6, s38
	v_mov_b32_e32 v67, 0
	s_waitcnt vmcnt(0) lgkmcnt(0)
	v_lshl_add_u64 v[2:3], v[58:59], 0, s[14:15]
	v_lshl_add_u64 v[2:3], v[2:3], 0, v[76:77]
	v_lshl_add_u64 v[50:51], v[2:3], 0, s[8:9]
	s_add_i32 s100, s6, 0
	s_ashr_i32 s101, s100, 31
	s_lshl_b64 s[100:101], s[100:101], 11
	v_lshl_add_u64 v[252:253], v[50:51], 0, s[100:101]
	global_load_dwordx4 v[244:247], v[252:253], off offset:16
	global_load_dwordx4 v[248:251], v[252:253], off
	s_add_i32 s100, s6, 1
	s_ashr_i32 s101, s100, 31
	s_lshl_b64 s[100:101], s[100:101], 11
	v_lshl_add_u64 v[252:253], v[50:51], 0, s[100:101]
	global_load_dwordx4 v[244:247], v[252:253], off offset:16
	global_load_dwordx4 v[248:251], v[252:253], off
	s_add_i32 s100, s6, 2
	s_ashr_i32 s101, s100, 31
	s_lshl_b64 s[100:101], s[100:101], 11
	v_lshl_add_u64 v[252:253], v[50:51], 0, s[100:101]
	global_load_dwordx4 v[244:247], v[252:253], off offset:16
	global_load_dwordx4 v[248:251], v[252:253], off
	s_add_i32 s100, s6, 3
	s_ashr_i32 s101, s100, 31
	s_lshl_b64 s[100:101], s[100:101], 11
	v_lshl_add_u64 v[252:253], v[50:51], 0, s[100:101]
	global_load_dwordx4 v[244:247], v[252:253], off offset:16
	global_load_dwordx4 v[248:251], v[252:253], off
	s_add_i32 s100, s6, 4
	s_ashr_i32 s101, s100, 31
	s_lshl_b64 s[100:101], s[100:101], 11
	v_lshl_add_u64 v[252:253], v[50:51], 0, s[100:101]
	global_load_dwordx4 v[244:247], v[252:253], off offset:16
	global_load_dwordx4 v[248:251], v[252:253], off
	s_add_i32 s100, s6, 5
	s_ashr_i32 s101, s100, 31
	s_lshl_b64 s[100:101], s[100:101], 11
	v_lshl_add_u64 v[252:253], v[50:51], 0, s[100:101]
	global_load_dwordx4 v[244:247], v[252:253], off offset:16
	global_load_dwordx4 v[248:251], v[252:253], off
	s_add_i32 s100, s6, 6
	s_ashr_i32 s101, s100, 31
	s_lshl_b64 s[100:101], s[100:101], 11
	v_lshl_add_u64 v[252:253], v[50:51], 0, s[100:101]
	global_load_dwordx4 v[244:247], v[252:253], off offset:16
	global_load_dwordx4 v[248:251], v[252:253], off
	s_add_i32 s100, s6, 7
	s_ashr_i32 s101, s100, 31
	s_lshl_b64 s[100:101], s[100:101], 11
	v_lshl_add_u64 v[252:253], v[50:51], 0, s[100:101]
	global_load_dwordx4 v[244:247], v[252:253], off offset:16
	global_load_dwordx4 v[248:251], v[252:253], off
	s_cmp_ge_i32 s6, s38
	s_cbranch_scc1 .LBB0_419
	s_ashr_i32 s7, s6, 31
	s_lshl_b64 s[14:15], s[6:7], 11
	v_lshl_add_u64 v[8:9], v[50:51], 0, s[14:15]
	global_load_dwordx4 v[0:3], v[8:9], off offset:16
	global_load_dwordx4 v[4:7], v[8:9], off
	s_waitcnt vmcnt(1)
	v_mov_b32_e32 v64, v1
	v_mov_b32_e32 v1, v2
	v_mov_b32_e32 v65, v3
	s_waitcnt vmcnt(0)
	v_mov_b32_e32 v62, v4
	v_mov_b32_e32 v66, v5
	v_mov_b32_e32 v63, v6
	v_mov_b32_e32 v67, v7
	s_add_i32 s14, s6, 1
	s_cmp_lt_i32 s14, s38
	s_mov_b64 s[16:17], -1
	s_cbranch_scc0 .LBB0_420

.LBB0_1152:
	flat_load_dwordx2 v[58:59], v[78:79] offset:216
	flat_load_dwordx2 v[60:61], v[78:79] offset:152
	s_and_b32 s41, s3, 63
	s_and_b32 s8, s3, 0xffffffc0
	s_add_i32 s18, s41, 7
	s_ashr_i32 s9, s8, 31
	s_lshr_b32 s20, s18, 3
	s_lshl_b64 s[18:19], s[8:9], 11
	s_mul_i32 s8, s20, s23
	s_add_i32 s9, s8, s20
	s_min_i32 s42, s9, s41
	v_mov_b32_e32 v0, 1.0
	v_mov_b32_e32 v64, 0
	v_mov_b32_e32 v1, 1.0
	v_mov_b32_e32 v65, 0
	v_mov_b32_e32 v62, 1.0
	v_mov_b32_e32 v66, 0
	v_mov_b32_e32 v63, 1.0
	s_cmp_ge_i32 s8, s42
	v_mov_b32_e32 v67, 0
	s_waitcnt vmcnt(0) lgkmcnt(0)
	v_lshl_add_u64 v[2:3], v[58:59], 0, s[18:19]
	v_lshl_add_u64 v[2:3], v[2:3], 0, v[76:77]
	v_lshl_add_u64 v[50:51], v[2:3], 0, s[10:11]
	s_add_i32 s100, s8, 0
	s_ashr_i32 s101, s100, 31
	s_lshl_b64 s[100:101], s[100:101], 11
	v_lshl_add_u64 v[252:253], v[50:51], 0, s[100:101]
	global_load_dwordx4 v[244:247], v[252:253], off offset:16
	global_load_dwordx4 v[248:251], v[252:253], off
	s_add_i32 s100, s8, 1
	s_ashr_i32 s101, s100, 31
	s_lshl_b64 s[100:101], s[100:101], 11
	v_lshl_add_u64 v[252:253], v[50:51], 0, s[100:101]
	global_load_dwordx4 v[244:247], v[252:253], off offset:16
	global_load_dwordx4 v[248:251], v[252:253], off
	s_add_i32 s100, s8, 2
	s_ashr_i32 s101, s100, 31
	s_lshl_b64 s[100:101], s[100:101], 11
	v_lshl_add_u64 v[252:253], v[50:51], 0, s[100:101]
	global_load_dwordx4 v[244:247], v[252:253], off offset:16
	global_load_dwordx4 v[248:251], v[252:253], off
	s_add_i32 s100, s8, 3
	s_ashr_i32 s101, s100, 31
	s_lshl_b64 s[100:101], s[100:101], 11
	v_lshl_add_u64 v[252:253], v[50:51], 0, s[100:101]
	global_load_dwordx4 v[244:247], v[252:253], off offset:16
	global_load_dwordx4 v[248:251], v[252:253], off
	s_add_i32 s100, s8, 4
	s_ashr_i32 s101, s100, 31
	s_lshl_b64 s[100:101], s[100:101], 11
	v_lshl_add_u64 v[252:253], v[50:51], 0, s[100:101]
	global_load_dwordx4 v[244:247], v[252:253], off offset:16
	global_load_dwordx4 v[248:251], v[252:253], off
	s_add_i32 s100, s8, 5
	s_ashr_i32 s101, s100, 31
	s_lshl_b64 s[100:101], s[100:101], 11
	v_lshl_add_u64 v[252:253], v[50:51], 0, s[100:101]
	global_load_dwordx4 v[244:247], v[252:253], off offset:16
	global_load_dwordx4 v[248:251], v[252:253], off
	s_add_i32 s100, s8, 6
	s_ashr_i32 s101, s100, 31
	s_lshl_b64 s[100:101], s[100:101], 11
	v_lshl_add_u64 v[252:253], v[50:51], 0, s[100:101]
	global_load_dwordx4 v[244:247], v[252:253], off offset:16
	global_load_dwordx4 v[248:251], v[252:253], off
	s_add_i32 s100, s8, 7
	s_ashr_i32 s101, s100, 31
	s_lshl_b64 s[100:101], s[100:101], 11
	v_lshl_add_u64 v[252:253], v[50:51], 0, s[100:101]
	global_load_dwordx4 v[244:247], v[252:253], off offset:16
	global_load_dwordx4 v[248:251], v[252:253], off
	s_cmp_ge_i32 s8, s42
	s_cbranch_scc1 .LBB0_1156
	s_ashr_i32 s9, s8, 31
	s_lshl_b64 s[18:19], s[8:9], 11
	v_lshl_add_u64 v[8:9], v[50:51], 0, s[18:19]
	global_load_dwordx4 v[0:3], v[8:9], off offset:16
	global_load_dwordx4 v[4:7], v[8:9], off
	s_waitcnt vmcnt(1)
	v_mov_b32_e32 v64, v1
	v_mov_b32_e32 v1, v2
	v_mov_b32_e32 v65, v3
	s_waitcnt vmcnt(0)
	v_mov_b32_e32 v62, v4
	v_mov_b32_e32 v66, v5
	v_mov_b32_e32 v63, v6
	v_mov_b32_e32 v67, v7
	s_add_i32 s18, s8, 1
	s_cmp_lt_i32 s18, s42
	s_mov_b64 s[20:21], -1
	s_cbranch_scc0 .LBB0_1157
